# v32 + one L2 invalidate per XCD for the chain-output acquire (first workgroup of each XCD invalidates, the others wait for its flag)
# baseline (speedup 1.0000x reference)
; DI void phase_prep(const Params& p) {
;     ...
;   if (blockIdx.x == 0 && tid == 0) *(unsigned*)(p.ws + WS_END) = 0u;
;   { float* RS = (float*)(p.ws + WS_END + 8192); const int i = blockIdx.x * 512 + tid; if (i < NTOK) RS[i] = 0.f; }
.LBB0_17:
	s_or_b64 exec, exec, s[4:5]
	v_or_b32_e32 v0, s2, v202
	v_cmp_eq_u32_e32 vcc, 0, v0
	s_and_saveexec_b64 s[4:5], vcc
	s_cbranch_execz .LBB0_19
	v_mov_b32_e32 v0, 0x32000000
	v_mov_b32_e32 v1, 0
	global_store_dword v0, v1, s[58:59]
	global_store_dword v0, v1, s[58:59] offset:64
	global_store_dword v0, v1, s[58:59] offset:128
	global_store_dword v0, v1, s[58:59] offset:132
	global_store_dword v0, v1, s[58:59] offset:136
	global_store_dword v0, v1, s[58:59] offset:140
	global_store_dword v0, v1, s[58:59] offset:144
	global_store_dword v0, v1, s[58:59] offset:148
	global_store_dword v0, v1, s[58:59] offset:152
	global_store_dword v0, v1, s[58:59] offset:156

; DI void phase_mixer(const Params& p) {
;     ...
;   for (;;) {
;     __syncthreads();
;     if (threadIdx.x == 0) *sItem = (int)atomicAdd(ctr, 1u);
;     __syncthreads();
;     const int it = *sItem;
;     if (it >= 48 + 2048) break;
;     if (it < 48) hgrn_item(p, it); else attn_item(p, it - 48);
.Lcq_item:
	s_and_saveexec_b64 s[0:1], s[84:85]
	s_cbranch_execz .Lcq_go
	s_cmp_eq_u32 s32, 1
	s_cbranch_scc1 .Lcq_go
	s_mov_b32 s32, 1
	v_readlane_b32 s3, v236, 11
	s_nop 3
	s_and_b32 s3, s3, 7
	s_lshl_b32 s3, s3, 2
	s_addk_i32 s3, 0x80
	v_mov_b32_e32 v0, s3
	v_mov_b32_e32 v1, 1
	global_atomic_add v1, v0, v1, s[82:83] sc0
	s_waitcnt vmcnt(0)
	v_readfirstlane_b32 s4, v1
	s_cmp_eq_u32 s4, 0
	s_cbranch_scc0 .Lcq_follow
	v_mov_b32_e32 v2, 0
.Lcq_spin:
	global_load_dword v1, v2, s[82:83] offset:64 sc1
	s_waitcnt vmcnt(0)
	v_readfirstlane_b32 s4, v1
	s_cmp_ge_u32 s4, 48
	s_cbranch_scc1 .Lcq_ok
	s_sleep 1
	s_branch .Lcq_spin
.Lcq_ok:
	buffer_inv sc1
	s_waitcnt vmcnt(0)
	v_mov_b32_e32 v1, 0x10000
	global_atomic_add v0, v1, s[82:83]
	s_branch .Lcq_go
.Lcq_follow:
	global_load_dword v1, v0, s[82:83] sc1
	s_waitcnt vmcnt(0)
	v_readfirstlane_b32 s4, v1
	s_cmp_ge_u32 s4, 0x10000
	s_cbranch_scc1 .Lcq_fok
	s_sleep 1
	s_branch .Lcq_follow
.Lcq_fok:
	buffer_inv sc0
	s_waitcnt vmcnt(0)
